# GEMM k-loops: s_setprio inverted (load segment raised to 1, MMA segment at 0), reset to 0 at phase exit
# speedup vs baseline: 1.0011x; 1.0011x over previous
.LBB0_176:
	s_add_u32 s2, s14, 0xfffc0080
	s_addc_u32 s3, s15, -1
	s_add_i32 s47, 0, 0x10000
	s_cmp_eq_u32 s46, 12
	s_cselect_b32 s25, s7, s3
	s_cselect_b32 s24, s11, s2
	v_add_u32_e32 v0, s47, v155
	s_cselect_b32 s3, s13, s33
	s_cselect_b32 s2, s29, s31
	s_add_i32 s54, 0, 0x14000
	ds_read_b128 v[50:53], v0
	ds_read_b128 v[54:57], v0 offset:1024
	ds_read_b128 v[58:61], v0 offset:2048
	ds_read_b128 v[62:65], v0 offset:3072
	v_add_u32_e32 v0, s54, v155
	ds_read_b128 v[176:179], v0
	ds_read_b128 v[188:191], v0 offset:1024
	ds_read_b128 v[192:195], v0 offset:2048
	ds_read_b128 v[196:199], v0 offset:3072
	v_lshl_add_u64 v[180:181], s[14:15], 0, v[170:171]
	s_add_i32 m0, s90, 0xc000
	ds_read_b128 v[200:203], v186
	ds_read_b128 v[204:207], v186 offset:1024
	ds_read_b128 v[226:229], v186 offset:2048
	ds_read_b128 v[230:233], v186 offset:3072
	ds_read_b128 v[234:237], v186 offset:4096
	ds_read_b128 v[238:241], v186 offset:5120
	ds_read_b128 v[242:245], v186 offset:6144
	ds_read_b128 v[246:249], v186 offset:7168
	global_load_lds_dwordx4 v[180:181], off
	v_lshl_add_u64 v[180:181], s[14:15], 0, v[172:173]
	s_add_i32 m0, s90, 0xe000
	s_nop 0
	global_load_lds_dwordx4 v[180:181], off
	s_waitcnt vmcnt(8)
	s_waitcnt lgkmcnt(0)
	s_setprio 0
	s_barrier
	v_mfma_f32_16x16x32_bf16 v[142:145], v[50:53], v[200:203], v[142:145]
	v_mfma_f32_16x16x32_bf16 v[138:141], v[58:61], v[200:203], v[138:141]
	v_mfma_f32_16x16x32_bf16 v[126:129], v[50:53], v[226:229], v[126:129]
	v_mfma_f32_16x16x32_bf16 v[122:125], v[58:61], v[226:229], v[122:125]
	v_mfma_f32_16x16x32_bf16 v[110:113], v[50:53], v[234:237], v[110:113]
	v_mfma_f32_16x16x32_bf16 v[106:109], v[58:61], v[234:237], v[106:109]
	v_mfma_f32_16x16x32_bf16 v[94:97], v[50:53], v[242:245], v[94:97]
	v_mfma_f32_16x16x32_bf16 v[90:93], v[58:61], v[242:245], v[90:93]
	v_mfma_f32_16x16x32_bf16 v[142:145], v[54:57], v[204:207], v[142:145]
	v_mfma_f32_16x16x32_bf16 v[138:141], v[62:65], v[204:207], v[138:141]
	v_mfma_f32_16x16x32_bf16 v[126:129], v[54:57], v[230:233], v[126:129]
	v_mfma_f32_16x16x32_bf16 v[122:125], v[62:65], v[230:233], v[122:125]
	v_mfma_f32_16x16x32_bf16 v[110:113], v[54:57], v[238:241], v[110:113]
	v_mfma_f32_16x16x32_bf16 v[106:109], v[62:65], v[238:241], v[106:109]
	v_mfma_f32_16x16x32_bf16 v[94:97], v[54:57], v[246:249], v[94:97]
	v_mfma_f32_16x16x32_bf16 v[90:93], v[62:65], v[246:249], v[90:93]
	v_mfma_f32_16x16x32_bf16 v[134:137], v[176:179], v[200:203], v[134:137]
	v_mfma_f32_16x16x32_bf16 v[130:133], v[192:195], v[200:203], v[130:133]
	v_mfma_f32_16x16x32_bf16 v[118:121], v[176:179], v[226:229], v[118:121]
	v_mfma_f32_16x16x32_bf16 v[114:117], v[192:195], v[226:229], v[114:117]
	v_mfma_f32_16x16x32_bf16 v[102:105], v[176:179], v[234:237], v[102:105]
	v_mfma_f32_16x16x32_bf16 v[98:101], v[192:195], v[234:237], v[98:101]
	v_mfma_f32_16x16x32_bf16 v[86:89], v[176:179], v[242:245], v[86:89]
	v_mfma_f32_16x16x32_bf16 v[82:85], v[192:195], v[242:245], v[82:85]
	v_mfma_f32_16x16x32_bf16 v[134:137], v[188:191], v[204:207], v[134:137]
	v_mfma_f32_16x16x32_bf16 v[130:133], v[196:199], v[204:207], v[130:133]
	v_mfma_f32_16x16x32_bf16 v[118:121], v[188:191], v[230:233], v[118:121]
	v_mfma_f32_16x16x32_bf16 v[114:117], v[196:199], v[230:233], v[114:117]
	v_mfma_f32_16x16x32_bf16 v[102:105], v[188:191], v[238:241], v[102:105]
	v_mfma_f32_16x16x32_bf16 v[98:101], v[196:199], v[238:241], v[98:101]
	v_mfma_f32_16x16x32_bf16 v[86:89], v[188:191], v[246:249], v[86:89]
	v_mfma_f32_16x16x32_bf16 v[82:85], v[196:199], v[246:249], v[82:85]
	s_barrier
	s_setprio 1
	s_add_i32 s47, s47, s42
	v_lshl_add_u64 v[180:181], s[2:3], 0, v[146:147]
	s_mov_b32 m0, s47
	ds_read_b128 v[200:203], v186 offset:16384
	ds_read_b128 v[204:207], v186 offset:17408
	ds_read_b128 v[226:229], v186 offset:18432
	ds_read_b128 v[230:233], v186 offset:19456
	ds_read_b128 v[234:237], v186 offset:20480
	ds_read_b128 v[238:241], v186 offset:21504
	ds_read_b128 v[242:245], v186 offset:22528
	ds_read_b128 v[246:249], v186 offset:23552
	global_load_lds_dwordx4 v[180:181], off
	s_add_i32 m0, s47, 0x2000
	s_add_u32 s58, s2, 0x40000
	v_lshl_add_u64 v[222:223], s[2:3], 0, v[148:149]
	s_addc_u32 s59, s3, 0
	s_add_i32 s47, s54, s42
	global_load_lds_dwordx4 v[222:223], off
	v_lshl_add_u64 v[224:225], s[58:59], 0, v[146:147]
	s_mov_b32 m0, s47
	v_lshl_add_u64 v[250:251], s[24:25], 0, v[148:149]
	global_load_lds_dwordx4 v[224:225], off
	v_lshl_add_u64 v[224:225], s[58:59], 0, v[148:149]
	s_add_i32 m0, s47, 0x2000
	s_nop 0
	global_load_lds_dwordx4 v[224:225], off
	v_lshl_add_u64 v[224:225], s[24:25], 0, v[146:147]
	s_mov_b32 m0, s90
	s_nop 0
	global_load_lds_dwordx4 v[224:225], off
	s_mov_b32 m0, s91
	s_nop 0
	global_load_lds_dwordx4 v[250:251], off
	s_waitcnt vmcnt(8)
	s_waitcnt lgkmcnt(0)
	s_setprio 0
	s_barrier
	v_mfma_f32_16x16x32_bf16 v[78:81], v[50:53], v[200:203], v[78:81]
	v_mfma_f32_16x16x32_bf16 v[74:77], v[58:61], v[200:203], v[74:77]
	v_mfma_f32_16x16x32_bf16 v[46:49], v[50:53], v[226:229], v[46:49]
	v_mfma_f32_16x16x32_bf16 v[42:45], v[58:61], v[226:229], v[42:45]
	v_mfma_f32_16x16x32_bf16 v[30:33], v[50:53], v[234:237], v[30:33]
	v_mfma_f32_16x16x32_bf16 v[26:29], v[58:61], v[234:237], v[26:29]
	v_mfma_f32_16x16x32_bf16 v[14:17], v[50:53], v[242:245], v[14:17]
	v_mfma_f32_16x16x32_bf16 v[10:13], v[58:61], v[242:245], v[10:13]
	v_mfma_f32_16x16x32_bf16 v[78:81], v[54:57], v[204:207], v[78:81]
	v_mfma_f32_16x16x32_bf16 v[74:77], v[62:65], v[204:207], v[74:77]
	v_mfma_f32_16x16x32_bf16 v[46:49], v[54:57], v[230:233], v[46:49]
	v_mfma_f32_16x16x32_bf16 v[42:45], v[62:65], v[230:233], v[42:45]
	v_mfma_f32_16x16x32_bf16 v[30:33], v[54:57], v[238:241], v[30:33]
	v_mfma_f32_16x16x32_bf16 v[26:29], v[62:65], v[238:241], v[26:29]
	v_mfma_f32_16x16x32_bf16 v[14:17], v[54:57], v[246:249], v[14:17]
	v_mfma_f32_16x16x32_bf16 v[10:13], v[62:65], v[246:249], v[10:13]
	v_mfma_f32_16x16x32_bf16 v[38:41], v[176:179], v[226:229], v[38:41]
	v_mfma_f32_16x16x32_bf16 v[34:37], v[192:195], v[226:229], v[34:37]
	v_mfma_f32_16x16x32_bf16 v[22:25], v[176:179], v[234:237], v[22:25]
	v_mfma_f32_16x16x32_bf16 v[18:21], v[192:195], v[234:237], v[18:21]
	v_mfma_f32_16x16x32_bf16 v[6:9], v[176:179], v[242:245], v[6:9]
	v_mfma_f32_16x16x32_bf16 v[2:5], v[192:195], v[242:245], v[2:5]
	v_mfma_f32_16x16x32_bf16 v[50:53], v[176:179], v[200:203], v[70:73]
	v_mfma_f32_16x16x32_bf16 v[54:57], v[192:195], v[200:203], v[66:69]
	v_mfma_f32_16x16x32_bf16 v[38:41], v[188:191], v[230:233], v[38:41]
	v_mfma_f32_16x16x32_bf16 v[34:37], v[196:199], v[230:233], v[34:37]
	v_mfma_f32_16x16x32_bf16 v[22:25], v[188:191], v[238:241], v[22:25]
	v_mfma_f32_16x16x32_bf16 v[18:21], v[196:199], v[238:241], v[18:21]
	v_mfma_f32_16x16x32_bf16 v[6:9], v[188:191], v[246:249], v[6:9]
	v_mfma_f32_16x16x32_bf16 v[2:5], v[196:199], v[246:249], v[2:5]
	v_mfma_f32_16x16x32_bf16 v[50:53], v[188:191], v[204:207], v[50:53]
	v_mfma_f32_16x16x32_bf16 v[54:57], v[196:199], v[204:207], v[54:57]
	s_barrier
	s_setprio 1
	s_add_i32 s47, 0, 0x18000
	v_add_u32_e32 v0, s47, v155
	s_add_i32 s54, 0, 0x1c000
	ds_read_b128 v[58:61], v0
	ds_read_b128 v[62:65], v0 offset:1024
	ds_read_b128 v[66:69], v0 offset:2048
	ds_read_b128 v[70:73], v0 offset:3072
	v_add_u32_e32 v0, s54, v155
	ds_read_b128 v[176:179], v0
	ds_read_b128 v[188:191], v0 offset:1024
	ds_read_b128 v[192:195], v0 offset:2048
	ds_read_b128 v[196:199], v0 offset:3072
	s_add_u32 s24, s24, 0x40000
	s_addc_u32 s25, s25, 0
	s_mov_b32 m0, s74
	v_lshl_add_u64 v[218:219], s[24:25], 0, v[146:147]
	ds_read_b128 v[200:203], v186 offset:32768
	ds_read_b128 v[204:207], v186 offset:33792
	ds_read_b128 v[226:229], v186 offset:34816
	ds_read_b128 v[230:233], v186 offset:35840
	ds_read_b128 v[234:237], v186 offset:36864
	ds_read_b128 v[238:241], v186 offset:37888
	ds_read_b128 v[242:245], v186 offset:38912
	ds_read_b128 v[246:249], v186 offset:39936
	global_load_lds_dwordx4 v[218:219], off
	v_lshl_add_u64 v[218:219], s[24:25], 0, v[148:149]
	s_mov_b32 m0, s75
	s_nop 0
	global_load_lds_dwordx4 v[218:219], off
	s_waitcnt vmcnt(8)
	s_waitcnt lgkmcnt(0)
	s_setprio 0
	s_barrier
	v_mfma_f32_16x16x32_bf16 v[142:145], v[58:61], v[200:203], v[142:145]
	v_mfma_f32_16x16x32_bf16 v[138:141], v[66:69], v[200:203], v[138:141]
	v_mfma_f32_16x16x32_bf16 v[126:129], v[58:61], v[226:229], v[126:129]
	v_mfma_f32_16x16x32_bf16 v[122:125], v[66:69], v[226:229], v[122:125]
	v_mfma_f32_16x16x32_bf16 v[110:113], v[58:61], v[234:237], v[110:113]
	v_mfma_f32_16x16x32_bf16 v[106:109], v[66:69], v[234:237], v[106:109]
	v_mfma_f32_16x16x32_bf16 v[94:97], v[58:61], v[242:245], v[94:97]
	v_mfma_f32_16x16x32_bf16 v[90:93], v[66:69], v[242:245], v[90:93]
	v_mfma_f32_16x16x32_bf16 v[142:145], v[62:65], v[204:207], v[142:145]
	v_mfma_f32_16x16x32_bf16 v[138:141], v[70:73], v[204:207], v[138:141]
	v_mfma_f32_16x16x32_bf16 v[126:129], v[62:65], v[230:233], v[126:129]
	v_mfma_f32_16x16x32_bf16 v[122:125], v[70:73], v[230:233], v[122:125]
	v_mfma_f32_16x16x32_bf16 v[110:113], v[62:65], v[238:241], v[110:113]
	v_mfma_f32_16x16x32_bf16 v[106:109], v[70:73], v[238:241], v[106:109]
	v_mfma_f32_16x16x32_bf16 v[94:97], v[62:65], v[246:249], v[94:97]
	v_mfma_f32_16x16x32_bf16 v[90:93], v[70:73], v[246:249], v[90:93]
	v_mfma_f32_16x16x32_bf16 v[134:137], v[176:179], v[200:203], v[134:137]
	v_mfma_f32_16x16x32_bf16 v[130:133], v[192:195], v[200:203], v[130:133]
	v_mfma_f32_16x16x32_bf16 v[118:121], v[176:179], v[226:229], v[118:121]
	v_mfma_f32_16x16x32_bf16 v[114:117], v[192:195], v[226:229], v[114:117]
	v_mfma_f32_16x16x32_bf16 v[102:105], v[176:179], v[234:237], v[102:105]
	v_mfma_f32_16x16x32_bf16 v[98:101], v[192:195], v[234:237], v[98:101]
	v_mfma_f32_16x16x32_bf16 v[86:89], v[176:179], v[242:245], v[86:89]
	v_mfma_f32_16x16x32_bf16 v[82:85], v[192:195], v[242:245], v[82:85]
	v_mfma_f32_16x16x32_bf16 v[134:137], v[188:191], v[204:207], v[134:137]
	v_mfma_f32_16x16x32_bf16 v[130:133], v[196:199], v[204:207], v[130:133]
	v_mfma_f32_16x16x32_bf16 v[118:121], v[188:191], v[230:233], v[118:121]
	v_mfma_f32_16x16x32_bf16 v[114:117], v[196:199], v[230:233], v[114:117]
	v_mfma_f32_16x16x32_bf16 v[102:105], v[188:191], v[238:241], v[102:105]
	v_mfma_f32_16x16x32_bf16 v[98:101], v[196:199], v[238:241], v[98:101]
	v_mfma_f32_16x16x32_bf16 v[86:89], v[188:191], v[246:249], v[86:89]
	v_mfma_f32_16x16x32_bf16 v[82:85], v[196:199], v[246:249], v[82:85]
	s_barrier
	s_setprio 1
	s_add_i32 s24, s47, s42
	v_lshl_add_u64 v[180:181], v[180:181], 0, s[44:45]
	s_mov_b32 m0, s24
	ds_read_b128 v[200:203], v186 offset:49152
	ds_read_b128 v[204:207], v186 offset:50176
	ds_read_b128 v[226:229], v186 offset:51200
	ds_read_b128 v[230:233], v186 offset:52224
	ds_read_b128 v[234:237], v186 offset:53248
	ds_read_b128 v[238:241], v186 offset:54272
	ds_read_b128 v[242:245], v186 offset:55296
	ds_read_b128 v[246:249], v186 offset:56320
	global_load_lds_dwordx4 v[180:181], off
	s_add_i32 m0, s24, 0x2000
	s_add_u32 s2, s2, 0x40080
	v_lshl_add_u64 v[180:181], v[222:223], 0, s[44:45]
	s_addc_u32 s3, s3, 0
	s_add_i32 s24, s54, s42
	global_load_lds_dwordx4 v[180:181], off
	v_lshl_add_u64 v[180:181], s[2:3], 0, v[146:147]
	s_mov_b32 m0, s24
	s_nop 0
	global_load_lds_dwordx4 v[180:181], off
	v_lshl_add_u64 v[180:181], s[2:3], 0, v[148:149]
	s_add_i32 m0, s24, 0x2000
	s_nop 0
	global_load_lds_dwordx4 v[180:181], off
	v_lshl_add_u64 v[180:181], v[224:225], 0, s[44:45]
	s_mov_b32 m0, s20
	s_nop 0
	global_load_lds_dwordx4 v[180:181], off
	v_lshl_add_u64 v[180:181], v[250:251], 0, s[44:45]
	s_mov_b32 m0, s21
	s_nop 0
	global_load_lds_dwordx4 v[180:181], off
	s_waitcnt vmcnt(8)
	s_waitcnt lgkmcnt(0)
	s_setprio 0
	s_barrier
	v_mfma_f32_16x16x32_bf16 v[78:81], v[58:61], v[200:203], v[78:81]
	v_mfma_f32_16x16x32_bf16 v[74:77], v[66:69], v[200:203], v[74:77]
	v_mfma_f32_16x16x32_bf16 v[46:49], v[58:61], v[226:229], v[46:49]
	v_mfma_f32_16x16x32_bf16 v[42:45], v[66:69], v[226:229], v[42:45]
	v_mfma_f32_16x16x32_bf16 v[30:33], v[58:61], v[234:237], v[30:33]
	v_mfma_f32_16x16x32_bf16 v[26:29], v[66:69], v[234:237], v[26:29]
	v_mfma_f32_16x16x32_bf16 v[14:17], v[58:61], v[242:245], v[14:17]
	v_mfma_f32_16x16x32_bf16 v[10:13], v[66:69], v[242:245], v[10:13]
	v_mfma_f32_16x16x32_bf16 v[78:81], v[62:65], v[204:207], v[78:81]
	v_mfma_f32_16x16x32_bf16 v[74:77], v[70:73], v[204:207], v[74:77]
	v_mfma_f32_16x16x32_bf16 v[46:49], v[62:65], v[230:233], v[46:49]
	v_mfma_f32_16x16x32_bf16 v[42:45], v[70:73], v[230:233], v[42:45]
	v_mfma_f32_16x16x32_bf16 v[30:33], v[62:65], v[238:241], v[30:33]
	v_mfma_f32_16x16x32_bf16 v[26:29], v[70:73], v[238:241], v[26:29]
	v_mfma_f32_16x16x32_bf16 v[14:17], v[62:65], v[246:249], v[14:17]
	v_mfma_f32_16x16x32_bf16 v[10:13], v[70:73], v[246:249], v[10:13]
	v_mfma_f32_16x16x32_bf16 v[50:53], v[176:179], v[200:203], v[50:53]
	v_mfma_f32_16x16x32_bf16 v[70:73], v[188:191], v[204:207], v[50:53]
	v_mfma_f32_16x16x32_bf16 v[50:53], v[192:195], v[200:203], v[54:57]
	v_mfma_f32_16x16x32_bf16 v[38:41], v[176:179], v[226:229], v[38:41]
	v_mfma_f32_16x16x32_bf16 v[34:37], v[192:195], v[226:229], v[34:37]
	v_mfma_f32_16x16x32_bf16 v[22:25], v[176:179], v[234:237], v[22:25]
	v_mfma_f32_16x16x32_bf16 v[18:21], v[192:195], v[234:237], v[18:21]
	v_mfma_f32_16x16x32_bf16 v[6:9], v[176:179], v[242:245], v[6:9]
	v_mfma_f32_16x16x32_bf16 v[2:5], v[192:195], v[242:245], v[2:5]
	v_mfma_f32_16x16x32_bf16 v[66:69], v[196:199], v[204:207], v[50:53]
	v_mfma_f32_16x16x32_bf16 v[38:41], v[188:191], v[230:233], v[38:41]
	v_mfma_f32_16x16x32_bf16 v[34:37], v[196:199], v[230:233], v[34:37]
	v_mfma_f32_16x16x32_bf16 v[22:25], v[188:191], v[238:241], v[22:25]
	v_mfma_f32_16x16x32_bf16 v[18:21], v[196:199], v[238:241], v[18:21]
	v_mfma_f32_16x16x32_bf16 v[6:9], v[188:191], v[246:249], v[6:9]
	v_mfma_f32_16x16x32_bf16 v[2:5], v[196:199], v[246:249], v[2:5]
	s_barrier
	s_setprio 1
	s_add_i32 s46, s46, 2
	s_add_u32 s14, s14, 0x100
	s_addc_u32 s15, s15, 0
	s_add_u32 s31, s31, 0x100
	s_addc_u32 s33, s33, 0
	s_cmp_gt_u32 s46, 13
	s_cbranch_scc0 .LBB0_176
	s_and_b64 vcc, exec, s[22:23]
	s_cbranch_vccz .LBB0_179
	s_barrier

.LBB0_650:
	s_add_u32 s2, s4, 0x100
	s_addc_u32 s3, s5, 0
	s_add_i32 s49, 0, 0x10000
	s_cmp_eq_u32 s48, 12
	s_cselect_b32 s29, s17, s3
	s_cselect_b32 s28, s25, s2
	v_add_u32_e32 v0, s49, v135
	s_cselect_b32 s27, s15, s47
	s_cselect_b32 s26, s42, s46
	s_add_i32 s50, 0, 0x14000
	ds_read_b128 v[146:149], v0
	ds_read_b128 v[150:153], v0 offset:1024
	ds_read_b128 v[154:157], v0 offset:2048
	ds_read_b128 v[158:161], v0 offset:3072
	v_add_u32_e32 v0, s50, v135
	ds_read_b128 v[162:165], v0
	ds_read_b128 v[166:169], v0 offset:1024
	ds_read_b128 v[170:173], v0 offset:2048
	ds_read_b128 v[174:177], v0 offset:3072
	v_lshl_add_u64 v[142:143], s[4:5], 0, v[138:139]
	s_add_i32 m0, s23, 0xc000
	ds_read_b128 v[178:181], v144
	ds_read_b128 v[182:185], v144 offset:1024
	ds_read_b128 v[186:189], v144 offset:2048
	ds_read_b128 v[190:193], v144 offset:3072
	ds_read_b128 v[194:197], v144 offset:4096
	ds_read_b128 v[198:201], v144 offset:5120
	ds_read_b128 v[202:205], v144 offset:6144
	ds_read_b128 v[222:225], v144 offset:7168
	global_load_lds_dwordx4 v[142:143], off
	v_lshl_add_u64 v[142:143], s[4:5], 0, v[140:141]
	s_add_i32 m0, s23, 0xe000
	s_nop 0
	global_load_lds_dwordx4 v[142:143], off
	s_waitcnt vmcnt(8)
	s_waitcnt lgkmcnt(0)
	s_setprio 0
	s_barrier
	v_mfma_f32_16x16x32_bf16 v[126:129], v[146:149], v[178:181], v[126:129]
	v_mfma_f32_16x16x32_bf16 v[122:125], v[154:157], v[178:181], v[122:125]
	v_mfma_f32_16x16x32_bf16 v[110:113], v[146:149], v[186:189], v[110:113]
	v_mfma_f32_16x16x32_bf16 v[106:109], v[154:157], v[186:189], v[106:109]
	v_mfma_f32_16x16x32_bf16 v[94:97], v[146:149], v[194:197], v[94:97]
	v_mfma_f32_16x16x32_bf16 v[90:93], v[154:157], v[194:197], v[90:93]
	v_mfma_f32_16x16x32_bf16 v[78:81], v[146:149], v[202:205], v[78:81]
	v_mfma_f32_16x16x32_bf16 v[74:77], v[154:157], v[202:205], v[74:77]
	v_mfma_f32_16x16x32_bf16 v[126:129], v[150:153], v[182:185], v[126:129]
	v_mfma_f32_16x16x32_bf16 v[122:125], v[158:161], v[182:185], v[122:125]
	v_mfma_f32_16x16x32_bf16 v[110:113], v[150:153], v[190:193], v[110:113]
	v_mfma_f32_16x16x32_bf16 v[106:109], v[158:161], v[190:193], v[106:109]
	v_mfma_f32_16x16x32_bf16 v[94:97], v[150:153], v[198:201], v[94:97]
	v_mfma_f32_16x16x32_bf16 v[90:93], v[158:161], v[198:201], v[90:93]
	v_mfma_f32_16x16x32_bf16 v[78:81], v[150:153], v[222:225], v[78:81]
	v_mfma_f32_16x16x32_bf16 v[74:77], v[158:161], v[222:225], v[74:77]
	v_mfma_f32_16x16x32_bf16 v[118:121], v[162:165], v[178:181], v[118:121]
	v_mfma_f32_16x16x32_bf16 v[114:117], v[170:173], v[178:181], v[114:117]
	v_mfma_f32_16x16x32_bf16 v[102:105], v[162:165], v[186:189], v[102:105]
	v_mfma_f32_16x16x32_bf16 v[98:101], v[170:173], v[186:189], v[98:101]
	v_mfma_f32_16x16x32_bf16 v[86:89], v[162:165], v[194:197], v[86:89]
	v_mfma_f32_16x16x32_bf16 v[82:85], v[170:173], v[194:197], v[82:85]
	v_mfma_f32_16x16x32_bf16 v[70:73], v[162:165], v[202:205], v[70:73]
	v_mfma_f32_16x16x32_bf16 v[66:69], v[170:173], v[202:205], v[66:69]
	v_mfma_f32_16x16x32_bf16 v[118:121], v[166:169], v[182:185], v[118:121]
	v_mfma_f32_16x16x32_bf16 v[114:117], v[174:177], v[182:185], v[114:117]
	v_mfma_f32_16x16x32_bf16 v[102:105], v[166:169], v[190:193], v[102:105]
	v_mfma_f32_16x16x32_bf16 v[98:101], v[174:177], v[190:193], v[98:101]
	v_mfma_f32_16x16x32_bf16 v[86:89], v[166:169], v[198:201], v[86:89]
	v_mfma_f32_16x16x32_bf16 v[82:85], v[174:177], v[198:201], v[82:85]
	v_mfma_f32_16x16x32_bf16 v[70:73], v[166:169], v[222:225], v[70:73]
	v_mfma_f32_16x16x32_bf16 v[66:69], v[174:177], v[222:225], v[66:69]
	s_barrier
	s_setprio 1
	s_add_i32 s4, s49, s30
	v_lshl_add_u64 v[142:143], s[26:27], 0, v[130:131]
	s_mov_b32 m0, s4
	ds_read_b128 v[178:181], v144 offset:16384
	ds_read_b128 v[182:185], v144 offset:17408
	ds_read_b128 v[186:189], v144 offset:18432
	ds_read_b128 v[190:193], v144 offset:19456
	ds_read_b128 v[194:197], v144 offset:20480
	ds_read_b128 v[198:201], v144 offset:21504
	ds_read_b128 v[202:205], v144 offset:22528
	ds_read_b128 v[222:225], v144 offset:23552
	global_load_lds_dwordx4 v[142:143], off
	s_add_i32 m0, s4, 0x2000
	s_add_u32 s4, s26, 0x40000
	v_lshl_add_u64 v[206:207], s[26:27], 0, v[132:133]
	s_addc_u32 s5, s27, 0
	s_add_i32 s49, s50, s30
	global_load_lds_dwordx4 v[206:207], off
	v_lshl_add_u64 v[218:219], s[4:5], 0, v[130:131]
	s_mov_b32 m0, s49
	v_lshl_add_u64 v[226:227], s[28:29], 0, v[132:133]
	global_load_lds_dwordx4 v[218:219], off
	v_lshl_add_u64 v[218:219], s[4:5], 0, v[132:133]
	s_add_i32 m0, s49, 0x2000
	s_nop 0
	global_load_lds_dwordx4 v[218:219], off
	v_lshl_add_u64 v[218:219], s[28:29], 0, v[130:131]
	s_mov_b32 m0, s23
	s_nop 0
	global_load_lds_dwordx4 v[218:219], off
	s_mov_b32 m0, s31
	s_nop 0
	global_load_lds_dwordx4 v[226:227], off
	s_waitcnt vmcnt(8)
	s_waitcnt lgkmcnt(0)
	s_setprio 0
	s_barrier
	v_mfma_f32_16x16x32_bf16 v[62:65], v[146:149], v[178:181], v[62:65]
	v_mfma_f32_16x16x32_bf16 v[58:61], v[154:157], v[178:181], v[58:61]
	v_mfma_f32_16x16x32_bf16 v[46:49], v[146:149], v[186:189], v[46:49]
	v_mfma_f32_16x16x32_bf16 v[42:45], v[154:157], v[186:189], v[42:45]
	v_mfma_f32_16x16x32_bf16 v[30:33], v[146:149], v[194:197], v[30:33]
	v_mfma_f32_16x16x32_bf16 v[26:29], v[154:157], v[194:197], v[26:29]
	v_mfma_f32_16x16x32_bf16 v[14:17], v[146:149], v[202:205], v[14:17]
	v_mfma_f32_16x16x32_bf16 v[10:13], v[154:157], v[202:205], v[10:13]
	v_mfma_f32_16x16x32_bf16 v[62:65], v[150:153], v[182:185], v[62:65]
	v_mfma_f32_16x16x32_bf16 v[58:61], v[158:161], v[182:185], v[58:61]
	v_mfma_f32_16x16x32_bf16 v[46:49], v[150:153], v[190:193], v[46:49]
	v_mfma_f32_16x16x32_bf16 v[42:45], v[158:161], v[190:193], v[42:45]
	v_mfma_f32_16x16x32_bf16 v[30:33], v[150:153], v[198:201], v[30:33]
	v_mfma_f32_16x16x32_bf16 v[26:29], v[158:161], v[198:201], v[26:29]
	v_mfma_f32_16x16x32_bf16 v[14:17], v[150:153], v[222:225], v[14:17]
	v_mfma_f32_16x16x32_bf16 v[10:13], v[158:161], v[222:225], v[10:13]
	v_mfma_f32_16x16x32_bf16 v[54:57], v[162:165], v[178:181], v[54:57]
	v_mfma_f32_16x16x32_bf16 v[50:53], v[170:173], v[178:181], v[50:53]
	v_mfma_f32_16x16x32_bf16 v[38:41], v[162:165], v[186:189], v[38:41]
	v_mfma_f32_16x16x32_bf16 v[34:37], v[170:173], v[186:189], v[34:37]
	v_mfma_f32_16x16x32_bf16 v[22:25], v[162:165], v[194:197], v[22:25]
	v_mfma_f32_16x16x32_bf16 v[18:21], v[170:173], v[194:197], v[18:21]
	v_mfma_f32_16x16x32_bf16 v[6:9], v[162:165], v[202:205], v[6:9]
	v_mfma_f32_16x16x32_bf16 v[2:5], v[170:173], v[202:205], v[2:5]
	v_mfma_f32_16x16x32_bf16 v[54:57], v[166:169], v[182:185], v[54:57]
	v_mfma_f32_16x16x32_bf16 v[50:53], v[174:177], v[182:185], v[50:53]
	v_mfma_f32_16x16x32_bf16 v[38:41], v[166:169], v[190:193], v[38:41]
	v_mfma_f32_16x16x32_bf16 v[34:37], v[174:177], v[190:193], v[34:37]
	v_mfma_f32_16x16x32_bf16 v[22:25], v[166:169], v[198:201], v[22:25]
	v_mfma_f32_16x16x32_bf16 v[18:21], v[174:177], v[198:201], v[18:21]
	v_mfma_f32_16x16x32_bf16 v[6:9], v[166:169], v[222:225], v[6:9]
	v_mfma_f32_16x16x32_bf16 v[2:5], v[174:177], v[222:225], v[2:5]
	s_barrier
	s_setprio 1
	s_add_i32 s49, 0, 0x18000
	v_add_u32_e32 v0, s49, v135
	s_add_i32 s50, 0, 0x1c000
	ds_read_b128 v[146:149], v0
	ds_read_b128 v[150:153], v0 offset:1024
	ds_read_b128 v[154:157], v0 offset:2048
	ds_read_b128 v[158:161], v0 offset:3072
	v_add_u32_e32 v0, s50, v135
	ds_read_b128 v[162:165], v0
	ds_read_b128 v[166:169], v0 offset:1024
	ds_read_b128 v[170:173], v0 offset:2048
	ds_read_b128 v[174:177], v0 offset:3072
	s_add_u32 s4, s28, 0x40000
	s_addc_u32 s5, s29, 0
	s_mov_b32 m0, s33
	v_lshl_add_u64 v[228:229], s[4:5], 0, v[130:131]
	ds_read_b128 v[178:181], v144 offset:32768
	ds_read_b128 v[182:185], v144 offset:33792
	ds_read_b128 v[186:189], v144 offset:34816
	ds_read_b128 v[190:193], v144 offset:35840
	ds_read_b128 v[194:197], v144 offset:36864
	ds_read_b128 v[198:201], v144 offset:37888
	ds_read_b128 v[202:205], v144 offset:38912
	ds_read_b128 v[222:225], v144 offset:39936
	global_load_lds_dwordx4 v[228:229], off
	v_lshl_add_u64 v[228:229], s[4:5], 0, v[132:133]
	s_mov_b32 m0, s34
	s_nop 0
	global_load_lds_dwordx4 v[228:229], off
	s_waitcnt vmcnt(8)
	s_waitcnt lgkmcnt(0)
	s_setprio 0
	s_barrier
	v_mfma_f32_16x16x32_bf16 v[126:129], v[146:149], v[178:181], v[126:129]
	v_mfma_f32_16x16x32_bf16 v[122:125], v[154:157], v[178:181], v[122:125]
	v_mfma_f32_16x16x32_bf16 v[110:113], v[146:149], v[186:189], v[110:113]
	v_mfma_f32_16x16x32_bf16 v[106:109], v[154:157], v[186:189], v[106:109]
	v_mfma_f32_16x16x32_bf16 v[94:97], v[146:149], v[194:197], v[94:97]
	v_mfma_f32_16x16x32_bf16 v[90:93], v[154:157], v[194:197], v[90:93]
	v_mfma_f32_16x16x32_bf16 v[78:81], v[146:149], v[202:205], v[78:81]
	v_mfma_f32_16x16x32_bf16 v[74:77], v[154:157], v[202:205], v[74:77]
	v_mfma_f32_16x16x32_bf16 v[126:129], v[150:153], v[182:185], v[126:129]
	v_mfma_f32_16x16x32_bf16 v[122:125], v[158:161], v[182:185], v[122:125]
	v_mfma_f32_16x16x32_bf16 v[110:113], v[150:153], v[190:193], v[110:113]
	v_mfma_f32_16x16x32_bf16 v[106:109], v[158:161], v[190:193], v[106:109]
	v_mfma_f32_16x16x32_bf16 v[94:97], v[150:153], v[198:201], v[94:97]
	v_mfma_f32_16x16x32_bf16 v[90:93], v[158:161], v[198:201], v[90:93]
	v_mfma_f32_16x16x32_bf16 v[78:81], v[150:153], v[222:225], v[78:81]
	v_mfma_f32_16x16x32_bf16 v[74:77], v[158:161], v[222:225], v[74:77]
	v_mfma_f32_16x16x32_bf16 v[118:121], v[162:165], v[178:181], v[118:121]
	v_mfma_f32_16x16x32_bf16 v[114:117], v[170:173], v[178:181], v[114:117]
	v_mfma_f32_16x16x32_bf16 v[102:105], v[162:165], v[186:189], v[102:105]
	v_mfma_f32_16x16x32_bf16 v[98:101], v[170:173], v[186:189], v[98:101]
	v_mfma_f32_16x16x32_bf16 v[86:89], v[162:165], v[194:197], v[86:89]
	v_mfma_f32_16x16x32_bf16 v[82:85], v[170:173], v[194:197], v[82:85]
	v_mfma_f32_16x16x32_bf16 v[70:73], v[162:165], v[202:205], v[70:73]
	v_mfma_f32_16x16x32_bf16 v[66:69], v[170:173], v[202:205], v[66:69]
	v_mfma_f32_16x16x32_bf16 v[118:121], v[166:169], v[182:185], v[118:121]
	v_mfma_f32_16x16x32_bf16 v[114:117], v[174:177], v[182:185], v[114:117]
	v_mfma_f32_16x16x32_bf16 v[102:105], v[166:169], v[190:193], v[102:105]
	v_mfma_f32_16x16x32_bf16 v[98:101], v[174:177], v[190:193], v[98:101]
	v_mfma_f32_16x16x32_bf16 v[86:89], v[166:169], v[198:201], v[86:89]
	v_mfma_f32_16x16x32_bf16 v[82:85], v[174:177], v[198:201], v[82:85]
	v_mfma_f32_16x16x32_bf16 v[70:73], v[166:169], v[222:225], v[70:73]
	v_mfma_f32_16x16x32_bf16 v[66:69], v[174:177], v[222:225], v[66:69]
	s_barrier
	s_setprio 1
	s_add_i32 s4, s49, s30
	v_lshl_add_u64 v[142:143], v[142:143], 0, s[44:45]
	s_mov_b32 m0, s4
	ds_read_b128 v[178:181], v144 offset:49152
	ds_read_b128 v[182:185], v144 offset:50176
	ds_read_b128 v[186:189], v144 offset:51200
	ds_read_b128 v[190:193], v144 offset:52224
	ds_read_b128 v[194:197], v144 offset:53248
	ds_read_b128 v[198:201], v144 offset:54272
	ds_read_b128 v[202:205], v144 offset:55296
	ds_read_b128 v[222:225], v144 offset:56320
	global_load_lds_dwordx4 v[142:143], off
	s_add_i32 m0, s4, 0x2000
	s_add_u32 s4, s26, 0x40080
	v_lshl_add_u64 v[142:143], v[206:207], 0, s[44:45]
	s_addc_u32 s5, s27, 0
	s_add_i32 s26, s50, s30
	global_load_lds_dwordx4 v[142:143], off
	v_lshl_add_u64 v[142:143], s[4:5], 0, v[130:131]
	s_mov_b32 m0, s26
	s_nop 0
	global_load_lds_dwordx4 v[142:143], off
	v_lshl_add_u64 v[142:143], s[4:5], 0, v[132:133]
	s_add_i32 m0, s26, 0x2000
	s_nop 0
	global_load_lds_dwordx4 v[142:143], off
	v_lshl_add_u64 v[142:143], v[218:219], 0, s[44:45]
	s_mov_b32 m0, s37
	s_nop 0
	global_load_lds_dwordx4 v[142:143], off
	v_lshl_add_u64 v[142:143], v[226:227], 0, s[44:45]
	s_mov_b32 m0, s38
	s_nop 0
	global_load_lds_dwordx4 v[142:143], off
	s_waitcnt vmcnt(8)
	s_waitcnt lgkmcnt(0)
	s_setprio 0
	s_barrier
	v_mfma_f32_16x16x32_bf16 v[62:65], v[146:149], v[178:181], v[62:65]
	v_mfma_f32_16x16x32_bf16 v[58:61], v[154:157], v[178:181], v[58:61]
	v_mfma_f32_16x16x32_bf16 v[46:49], v[146:149], v[186:189], v[46:49]
	v_mfma_f32_16x16x32_bf16 v[42:45], v[154:157], v[186:189], v[42:45]
	v_mfma_f32_16x16x32_bf16 v[30:33], v[146:149], v[194:197], v[30:33]
	v_mfma_f32_16x16x32_bf16 v[26:29], v[154:157], v[194:197], v[26:29]
	v_mfma_f32_16x16x32_bf16 v[14:17], v[146:149], v[202:205], v[14:17]
	v_mfma_f32_16x16x32_bf16 v[10:13], v[154:157], v[202:205], v[10:13]
	v_mfma_f32_16x16x32_bf16 v[62:65], v[150:153], v[182:185], v[62:65]
	v_mfma_f32_16x16x32_bf16 v[58:61], v[158:161], v[182:185], v[58:61]
	v_mfma_f32_16x16x32_bf16 v[46:49], v[150:153], v[190:193], v[46:49]
	v_mfma_f32_16x16x32_bf16 v[42:45], v[158:161], v[190:193], v[42:45]
	v_mfma_f32_16x16x32_bf16 v[30:33], v[150:153], v[198:201], v[30:33]
	v_mfma_f32_16x16x32_bf16 v[26:29], v[158:161], v[198:201], v[26:29]
	v_mfma_f32_16x16x32_bf16 v[14:17], v[150:153], v[222:225], v[14:17]
	v_mfma_f32_16x16x32_bf16 v[10:13], v[158:161], v[222:225], v[10:13]
	v_mfma_f32_16x16x32_bf16 v[54:57], v[162:165], v[178:181], v[54:57]
	v_mfma_f32_16x16x32_bf16 v[50:53], v[170:173], v[178:181], v[50:53]
	v_mfma_f32_16x16x32_bf16 v[38:41], v[162:165], v[186:189], v[38:41]
	v_mfma_f32_16x16x32_bf16 v[34:37], v[170:173], v[186:189], v[34:37]
	v_mfma_f32_16x16x32_bf16 v[22:25], v[162:165], v[194:197], v[22:25]
	v_mfma_f32_16x16x32_bf16 v[18:21], v[170:173], v[194:197], v[18:21]
	v_mfma_f32_16x16x32_bf16 v[6:9], v[162:165], v[202:205], v[6:9]
	v_mfma_f32_16x16x32_bf16 v[2:5], v[170:173], v[202:205], v[2:5]
	v_mfma_f32_16x16x32_bf16 v[54:57], v[166:169], v[182:185], v[54:57]
	v_mfma_f32_16x16x32_bf16 v[50:53], v[174:177], v[182:185], v[50:53]
	v_mfma_f32_16x16x32_bf16 v[38:41], v[166:169], v[190:193], v[38:41]
	v_mfma_f32_16x16x32_bf16 v[34:37], v[174:177], v[190:193], v[34:37]
	v_mfma_f32_16x16x32_bf16 v[22:25], v[166:169], v[198:201], v[22:25]
	v_mfma_f32_16x16x32_bf16 v[18:21], v[174:177], v[198:201], v[18:21]
	v_mfma_f32_16x16x32_bf16 v[6:9], v[166:169], v[222:225], v[6:9]
	v_mfma_f32_16x16x32_bf16 v[2:5], v[174:177], v[222:225], v[2:5]
	s_barrier
	s_setprio 1
	s_add_i32 s48, s48, 2
	s_add_u32 s46, s46, 0x100
	s_addc_u32 s47, s47, 0
	s_cmp_gt_u32 s48, 13
	s_mov_b64 s[4:5], s[2:3]
	s_cbranch_scc0 .LBB0_650
	s_and_b64 vcc, exec, s[12:13]
	s_cbranch_vccz .LBB0_653
	s_barrier

.LBB0_783:
	s_add_u32 s2, s4, 0xfffc0080
	s_addc_u32 s3, s5, -1
	s_add_i32 s48, 0, 0x10000
	s_cmp_eq_u32 s47, 12
	s_cselect_b32 s27, s17, s3
	s_cselect_b32 s26, s25, s2
	s_cselect_b32 s3, s15, s46
	s_cselect_b32 s2, s41, s42
	s_add_i32 s50, 0, 0x14000
	v_add_u32_e32 v154, s48, v140
	v_add_u32_e32 v170, s50, v140
	ds_read_b128 v[142:145], v154
	ds_read_b128 v[146:149], v154 offset:1024
	ds_read_b128 v[150:153], v154 offset:2048
	ds_read_b128 v[154:157], v154 offset:3072
	ds_read_b128 v[158:161], v170
	ds_read_b128 v[162:165], v170 offset:1024
	ds_read_b128 v[166:169], v170 offset:2048
	ds_read_b128 v[170:173], v170 offset:3072
	v_lshl_add_u64 v[206:207], s[4:5], 0, v[136:137]
	s_add_i32 m0, s23, 0xc000
	ds_read_b128 v[174:177], v141
	ds_read_b128 v[178:181], v141 offset:1024
	ds_read_b128 v[182:185], v141 offset:2048
	ds_read_b128 v[186:189], v141 offset:3072
	ds_read_b128 v[190:193], v141 offset:4096
	ds_read_b128 v[194:197], v141 offset:5120
	ds_read_b128 v[198:201], v141 offset:6144
	ds_read_b128 v[202:205], v141 offset:7168
	global_load_lds_dwordx4 v[206:207], off
	v_lshl_add_u64 v[206:207], s[4:5], 0, v[138:139]
	s_add_i32 m0, s23, 0xe000
	s_nop 0
	global_load_lds_dwordx4 v[206:207], off
	s_waitcnt vmcnt(8)
	s_waitcnt lgkmcnt(0)
	s_setprio 0
	s_barrier
	v_mfma_f32_16x16x32_bf16 v[122:125], v[142:145], v[174:177], v[122:125]
	v_mfma_f32_16x16x32_bf16 v[114:117], v[150:153], v[174:177], v[114:117]
	v_mfma_f32_16x16x32_bf16 v[106:109], v[142:145], v[182:185], v[106:109]
	v_mfma_f32_16x16x32_bf16 v[98:101], v[150:153], v[182:185], v[98:101]
	v_mfma_f32_16x16x32_bf16 v[90:93], v[142:145], v[190:193], v[90:93]
	v_mfma_f32_16x16x32_bf16 v[82:85], v[150:153], v[190:193], v[82:85]
	v_mfma_f32_16x16x32_bf16 v[74:77], v[142:145], v[198:201], v[74:77]
	v_mfma_f32_16x16x32_bf16 v[66:69], v[150:153], v[198:201], v[66:69]
	v_mfma_f32_16x16x32_bf16 v[122:125], v[146:149], v[178:181], v[122:125]
	v_mfma_f32_16x16x32_bf16 v[114:117], v[154:157], v[178:181], v[114:117]
	v_mfma_f32_16x16x32_bf16 v[106:109], v[146:149], v[186:189], v[106:109]
	v_mfma_f32_16x16x32_bf16 v[98:101], v[154:157], v[186:189], v[98:101]
	v_mfma_f32_16x16x32_bf16 v[90:93], v[146:149], v[194:197], v[90:93]
	v_mfma_f32_16x16x32_bf16 v[82:85], v[154:157], v[194:197], v[82:85]
	v_mfma_f32_16x16x32_bf16 v[74:77], v[146:149], v[202:205], v[74:77]
	v_mfma_f32_16x16x32_bf16 v[66:69], v[154:157], v[202:205], v[66:69]
	v_mfma_f32_16x16x32_bf16 v[126:129], v[158:161], v[174:177], v[126:129]
	v_mfma_f32_16x16x32_bf16 v[118:121], v[166:169], v[174:177], v[118:121]
	v_mfma_f32_16x16x32_bf16 v[110:113], v[158:161], v[182:185], v[110:113]
	v_mfma_f32_16x16x32_bf16 v[102:105], v[166:169], v[182:185], v[102:105]
	v_mfma_f32_16x16x32_bf16 v[94:97], v[158:161], v[190:193], v[94:97]
	v_mfma_f32_16x16x32_bf16 v[86:89], v[166:169], v[190:193], v[86:89]
	v_mfma_f32_16x16x32_bf16 v[78:81], v[158:161], v[198:201], v[78:81]
	v_mfma_f32_16x16x32_bf16 v[70:73], v[166:169], v[198:201], v[70:73]
	v_mfma_f32_16x16x32_bf16 v[126:129], v[162:165], v[178:181], v[126:129]
	v_mfma_f32_16x16x32_bf16 v[118:121], v[170:173], v[178:181], v[118:121]
	v_mfma_f32_16x16x32_bf16 v[110:113], v[162:165], v[186:189], v[110:113]
	v_mfma_f32_16x16x32_bf16 v[102:105], v[170:173], v[186:189], v[102:105]
	v_mfma_f32_16x16x32_bf16 v[94:97], v[162:165], v[194:197], v[94:97]
	v_mfma_f32_16x16x32_bf16 v[86:89], v[170:173], v[194:197], v[86:89]
	v_mfma_f32_16x16x32_bf16 v[78:81], v[162:165], v[202:205], v[78:81]
	v_mfma_f32_16x16x32_bf16 v[70:73], v[170:173], v[202:205], v[70:73]
	s_barrier
	s_setprio 1
	s_add_i32 s48, s48, s28
	v_lshl_add_u64 v[206:207], s[2:3], 0, v[132:133]
	s_mov_b32 m0, s48
	ds_read_b128 v[174:177], v141 offset:16384
	ds_read_b128 v[178:181], v141 offset:17408
	ds_read_b128 v[182:185], v141 offset:18432
	ds_read_b128 v[186:189], v141 offset:19456
	ds_read_b128 v[190:193], v141 offset:20480
	ds_read_b128 v[194:197], v141 offset:21504
	ds_read_b128 v[198:201], v141 offset:22528
	ds_read_b128 v[202:205], v141 offset:23552
	global_load_lds_dwordx4 v[206:207], off
	s_add_i32 m0, s48, 0x2000
	s_add_u32 s48, s2, 0x40000
	v_lshl_add_u64 v[218:219], s[2:3], 0, v[130:131]
	s_addc_u32 s49, s3, 0
	s_add_i32 s50, s50, s28
	global_load_lds_dwordx4 v[218:219], off
	v_lshl_add_u64 v[222:223], s[48:49], 0, v[132:133]
	s_mov_b32 m0, s50
	v_lshl_add_u64 v[224:225], s[26:27], 0, v[130:131]
	global_load_lds_dwordx4 v[222:223], off
	v_lshl_add_u64 v[222:223], s[48:49], 0, v[130:131]
	s_add_i32 m0, s50, 0x2000
	s_nop 0
	global_load_lds_dwordx4 v[222:223], off
	v_lshl_add_u64 v[222:223], s[26:27], 0, v[132:133]
	s_mov_b32 m0, s23
	s_nop 0
	global_load_lds_dwordx4 v[222:223], off
	s_mov_b32 m0, s31
	s_nop 0
	global_load_lds_dwordx4 v[224:225], off
	s_waitcnt vmcnt(8)
	s_waitcnt lgkmcnt(0)
	s_setprio 0
	s_barrier
	v_mfma_f32_16x16x32_bf16 v[58:61], v[142:145], v[174:177], v[58:61]
	v_mfma_f32_16x16x32_bf16 v[50:53], v[150:153], v[174:177], v[50:53]
	v_mfma_f32_16x16x32_bf16 v[42:45], v[142:145], v[182:185], v[42:45]
	v_mfma_f32_16x16x32_bf16 v[34:37], v[150:153], v[182:185], v[34:37]
	v_mfma_f32_16x16x32_bf16 v[26:29], v[142:145], v[190:193], v[26:29]
	v_mfma_f32_16x16x32_bf16 v[18:21], v[150:153], v[190:193], v[18:21]
	v_mfma_f32_16x16x32_bf16 v[10:13], v[142:145], v[198:201], v[10:13]
	v_mfma_f32_16x16x32_bf16 v[2:5], v[150:153], v[198:201], v[2:5]
	v_mfma_f32_16x16x32_bf16 v[58:61], v[146:149], v[178:181], v[58:61]
	v_mfma_f32_16x16x32_bf16 v[50:53], v[154:157], v[178:181], v[50:53]
	v_mfma_f32_16x16x32_bf16 v[42:45], v[146:149], v[186:189], v[42:45]
	v_mfma_f32_16x16x32_bf16 v[34:37], v[154:157], v[186:189], v[34:37]
	v_mfma_f32_16x16x32_bf16 v[26:29], v[146:149], v[194:197], v[26:29]
	v_mfma_f32_16x16x32_bf16 v[18:21], v[154:157], v[194:197], v[18:21]
	v_mfma_f32_16x16x32_bf16 v[10:13], v[146:149], v[202:205], v[10:13]
	v_mfma_f32_16x16x32_bf16 v[2:5], v[154:157], v[202:205], v[2:5]
	v_mfma_f32_16x16x32_bf16 v[62:65], v[158:161], v[174:177], v[62:65]
	v_mfma_f32_16x16x32_bf16 v[54:57], v[166:169], v[174:177], v[54:57]
	v_mfma_f32_16x16x32_bf16 v[46:49], v[158:161], v[182:185], v[46:49]
	v_mfma_f32_16x16x32_bf16 v[38:41], v[166:169], v[182:185], v[38:41]
	v_mfma_f32_16x16x32_bf16 v[30:33], v[158:161], v[190:193], v[30:33]
	v_mfma_f32_16x16x32_bf16 v[22:25], v[166:169], v[190:193], v[22:25]
	v_mfma_f32_16x16x32_bf16 v[14:17], v[158:161], v[198:201], v[14:17]
	v_mfma_f32_16x16x32_bf16 v[6:9], v[166:169], v[198:201], v[6:9]
	v_mfma_f32_16x16x32_bf16 v[62:65], v[162:165], v[178:181], v[62:65]
	v_mfma_f32_16x16x32_bf16 v[54:57], v[170:173], v[178:181], v[54:57]
	v_mfma_f32_16x16x32_bf16 v[46:49], v[162:165], v[186:189], v[46:49]
	v_mfma_f32_16x16x32_bf16 v[38:41], v[170:173], v[186:189], v[38:41]
	v_mfma_f32_16x16x32_bf16 v[30:33], v[162:165], v[194:197], v[30:33]
	v_mfma_f32_16x16x32_bf16 v[22:25], v[170:173], v[194:197], v[22:25]
	v_mfma_f32_16x16x32_bf16 v[14:17], v[162:165], v[202:205], v[14:17]
	v_mfma_f32_16x16x32_bf16 v[6:9], v[170:173], v[202:205], v[6:9]
	s_barrier
	s_setprio 1
	s_add_i32 s48, 0, 0x18000
	s_add_i32 s49, 0, 0x1c000
	v_add_u32_e32 v154, s48, v140
	v_add_u32_e32 v170, s49, v140
	ds_read_b128 v[142:145], v154
	ds_read_b128 v[146:149], v154 offset:1024
	ds_read_b128 v[150:153], v154 offset:2048
	ds_read_b128 v[154:157], v154 offset:3072
	ds_read_b128 v[158:161], v170
	ds_read_b128 v[162:165], v170 offset:1024
	ds_read_b128 v[166:169], v170 offset:2048
	ds_read_b128 v[170:173], v170 offset:3072
	s_add_u32 s26, s26, 0x40000
	s_addc_u32 s27, s27, 0
	s_mov_b32 m0, s33
	v_lshl_add_u64 v[226:227], s[26:27], 0, v[132:133]
	ds_read_b128 v[174:177], v141 offset:32768
	ds_read_b128 v[178:181], v141 offset:33792
	ds_read_b128 v[182:185], v141 offset:34816
	ds_read_b128 v[186:189], v141 offset:35840
	ds_read_b128 v[190:193], v141 offset:36864
	ds_read_b128 v[194:197], v141 offset:37888
	ds_read_b128 v[198:201], v141 offset:38912
	ds_read_b128 v[202:205], v141 offset:39936
	global_load_lds_dwordx4 v[226:227], off
	v_lshl_add_u64 v[226:227], s[26:27], 0, v[130:131]
	s_mov_b32 m0, s34
	s_nop 0
	global_load_lds_dwordx4 v[226:227], off
	s_waitcnt vmcnt(8)
	s_waitcnt lgkmcnt(0)
	s_setprio 0
	s_barrier
	v_mfma_f32_16x16x32_bf16 v[122:125], v[142:145], v[174:177], v[122:125]
	v_mfma_f32_16x16x32_bf16 v[114:117], v[150:153], v[174:177], v[114:117]
	v_mfma_f32_16x16x32_bf16 v[106:109], v[142:145], v[182:185], v[106:109]
	v_mfma_f32_16x16x32_bf16 v[98:101], v[150:153], v[182:185], v[98:101]
	v_mfma_f32_16x16x32_bf16 v[90:93], v[142:145], v[190:193], v[90:93]
	v_mfma_f32_16x16x32_bf16 v[82:85], v[150:153], v[190:193], v[82:85]
	v_mfma_f32_16x16x32_bf16 v[74:77], v[142:145], v[198:201], v[74:77]
	v_mfma_f32_16x16x32_bf16 v[66:69], v[150:153], v[198:201], v[66:69]
	v_mfma_f32_16x16x32_bf16 v[122:125], v[146:149], v[178:181], v[122:125]
	v_mfma_f32_16x16x32_bf16 v[114:117], v[154:157], v[178:181], v[114:117]
	v_mfma_f32_16x16x32_bf16 v[106:109], v[146:149], v[186:189], v[106:109]
	v_mfma_f32_16x16x32_bf16 v[98:101], v[154:157], v[186:189], v[98:101]
	v_mfma_f32_16x16x32_bf16 v[90:93], v[146:149], v[194:197], v[90:93]
	v_mfma_f32_16x16x32_bf16 v[82:85], v[154:157], v[194:197], v[82:85]
	v_mfma_f32_16x16x32_bf16 v[74:77], v[146:149], v[202:205], v[74:77]
	v_mfma_f32_16x16x32_bf16 v[66:69], v[154:157], v[202:205], v[66:69]
	v_mfma_f32_16x16x32_bf16 v[126:129], v[158:161], v[174:177], v[126:129]
	v_mfma_f32_16x16x32_bf16 v[118:121], v[166:169], v[174:177], v[118:121]
	v_mfma_f32_16x16x32_bf16 v[110:113], v[158:161], v[182:185], v[110:113]
	v_mfma_f32_16x16x32_bf16 v[102:105], v[166:169], v[182:185], v[102:105]
	v_mfma_f32_16x16x32_bf16 v[94:97], v[158:161], v[190:193], v[94:97]
	v_mfma_f32_16x16x32_bf16 v[86:89], v[166:169], v[190:193], v[86:89]
	v_mfma_f32_16x16x32_bf16 v[78:81], v[158:161], v[198:201], v[78:81]
	v_mfma_f32_16x16x32_bf16 v[70:73], v[166:169], v[198:201], v[70:73]
	v_mfma_f32_16x16x32_bf16 v[126:129], v[162:165], v[178:181], v[126:129]
	v_mfma_f32_16x16x32_bf16 v[118:121], v[170:173], v[178:181], v[118:121]
	v_mfma_f32_16x16x32_bf16 v[110:113], v[162:165], v[186:189], v[110:113]
	v_mfma_f32_16x16x32_bf16 v[102:105], v[170:173], v[186:189], v[102:105]
	v_mfma_f32_16x16x32_bf16 v[94:97], v[162:165], v[194:197], v[94:97]
	v_mfma_f32_16x16x32_bf16 v[86:89], v[170:173], v[194:197], v[86:89]
	v_mfma_f32_16x16x32_bf16 v[78:81], v[162:165], v[202:205], v[78:81]
	v_mfma_f32_16x16x32_bf16 v[70:73], v[170:173], v[202:205], v[70:73]
	s_barrier
	s_setprio 1
	s_add_i32 s26, s48, s28
	v_lshl_add_u64 v[206:207], v[206:207], 0, s[44:45]
	s_mov_b32 m0, s26
	ds_read_b128 v[174:177], v141 offset:49152
	ds_read_b128 v[178:181], v141 offset:50176
	ds_read_b128 v[182:185], v141 offset:51200
	ds_read_b128 v[186:189], v141 offset:52224
	ds_read_b128 v[190:193], v141 offset:53248
	ds_read_b128 v[194:197], v141 offset:54272
	ds_read_b128 v[198:201], v141 offset:55296
	ds_read_b128 v[202:205], v141 offset:56320
	global_load_lds_dwordx4 v[206:207], off
	s_add_i32 m0, s26, 0x2000
	s_add_u32 s2, s2, 0x40080
	v_lshl_add_u64 v[206:207], v[218:219], 0, s[44:45]
	s_addc_u32 s3, s3, 0
	s_add_i32 s26, s49, s28
	global_load_lds_dwordx4 v[206:207], off
	v_lshl_add_u64 v[206:207], s[2:3], 0, v[132:133]
	s_mov_b32 m0, s26
	s_nop 0
	global_load_lds_dwordx4 v[206:207], off
	v_lshl_add_u64 v[206:207], s[2:3], 0, v[130:131]
	s_add_i32 m0, s26, 0x2000
	s_nop 0
	global_load_lds_dwordx4 v[206:207], off
	v_lshl_add_u64 v[206:207], v[222:223], 0, s[44:45]
	s_mov_b32 m0, s35
	s_nop 0
	global_load_lds_dwordx4 v[206:207], off
	v_lshl_add_u64 v[206:207], v[224:225], 0, s[44:45]
	s_mov_b32 m0, s36
	s_nop 0
	global_load_lds_dwordx4 v[206:207], off
	s_waitcnt vmcnt(8)
	s_waitcnt lgkmcnt(0)
	s_setprio 0
	s_barrier
	v_mfma_f32_16x16x32_bf16 v[58:61], v[142:145], v[174:177], v[58:61]
	v_mfma_f32_16x16x32_bf16 v[50:53], v[150:153], v[174:177], v[50:53]
	v_mfma_f32_16x16x32_bf16 v[42:45], v[142:145], v[182:185], v[42:45]
	v_mfma_f32_16x16x32_bf16 v[34:37], v[150:153], v[182:185], v[34:37]
	v_mfma_f32_16x16x32_bf16 v[26:29], v[142:145], v[190:193], v[26:29]
	v_mfma_f32_16x16x32_bf16 v[18:21], v[150:153], v[190:193], v[18:21]
	v_mfma_f32_16x16x32_bf16 v[10:13], v[142:145], v[198:201], v[10:13]
	v_mfma_f32_16x16x32_bf16 v[2:5], v[150:153], v[198:201], v[2:5]
	v_mfma_f32_16x16x32_bf16 v[58:61], v[146:149], v[178:181], v[58:61]
	v_mfma_f32_16x16x32_bf16 v[50:53], v[154:157], v[178:181], v[50:53]
	v_mfma_f32_16x16x32_bf16 v[42:45], v[146:149], v[186:189], v[42:45]
	v_mfma_f32_16x16x32_bf16 v[34:37], v[154:157], v[186:189], v[34:37]
	v_mfma_f32_16x16x32_bf16 v[26:29], v[146:149], v[194:197], v[26:29]
	v_mfma_f32_16x16x32_bf16 v[18:21], v[154:157], v[194:197], v[18:21]
	v_mfma_f32_16x16x32_bf16 v[10:13], v[146:149], v[202:205], v[10:13]
	v_mfma_f32_16x16x32_bf16 v[2:5], v[154:157], v[202:205], v[2:5]
	v_mfma_f32_16x16x32_bf16 v[62:65], v[158:161], v[174:177], v[62:65]
	v_mfma_f32_16x16x32_bf16 v[54:57], v[166:169], v[174:177], v[54:57]
	v_mfma_f32_16x16x32_bf16 v[46:49], v[158:161], v[182:185], v[46:49]
	v_mfma_f32_16x16x32_bf16 v[38:41], v[166:169], v[182:185], v[38:41]
	v_mfma_f32_16x16x32_bf16 v[30:33], v[158:161], v[190:193], v[30:33]
	v_mfma_f32_16x16x32_bf16 v[22:25], v[166:169], v[190:193], v[22:25]
	v_mfma_f32_16x16x32_bf16 v[14:17], v[158:161], v[198:201], v[14:17]
	v_mfma_f32_16x16x32_bf16 v[6:9], v[166:169], v[198:201], v[6:9]
	v_mfma_f32_16x16x32_bf16 v[62:65], v[162:165], v[178:181], v[62:65]
	v_mfma_f32_16x16x32_bf16 v[54:57], v[170:173], v[178:181], v[54:57]
	v_mfma_f32_16x16x32_bf16 v[46:49], v[162:165], v[186:189], v[46:49]
	v_mfma_f32_16x16x32_bf16 v[38:41], v[170:173], v[186:189], v[38:41]
	v_mfma_f32_16x16x32_bf16 v[30:33], v[162:165], v[194:197], v[30:33]
	v_mfma_f32_16x16x32_bf16 v[22:25], v[170:173], v[194:197], v[22:25]
	v_mfma_f32_16x16x32_bf16 v[14:17], v[162:165], v[202:205], v[14:17]
	v_mfma_f32_16x16x32_bf16 v[6:9], v[170:173], v[202:205], v[6:9]
	s_barrier
	s_setprio 1
	s_add_i32 s47, s47, 2
	s_add_u32 s4, s4, 0x100
	s_addc_u32 s5, s5, 0
	s_add_u32 s42, s42, 0x100
	s_addc_u32 s46, s46, 0
	s_cmp_gt_u32 s47, 13
	s_cbranch_scc0 .LBB0_783
	s_and_b64 vcc, exec, s[12:13]
	s_cbranch_vccz .LBB0_786
	s_barrier

.LBB0_849:
	s_add_u32 s2, s18, 0x100
	s_addc_u32 s3, s19, 0
	s_add_i32 s47, 0, 0x10000
	s_cmp_eq_u32 s46, 40
	s_cselect_b32 s23, s9, s3
	s_cselect_b32 s22, s8, s2
	v_add_u32_e32 v0, s47, v135
	s_cselect_b32 s21, s15, s42
	s_cselect_b32 s20, s14, s17
	s_add_i32 s48, 0, 0x14000
	ds_read_b128 v[146:149], v0
	ds_read_b128 v[150:153], v0 offset:1024
	ds_read_b128 v[154:157], v0 offset:2048
	ds_read_b128 v[158:161], v0 offset:3072
	v_add_u32_e32 v0, s48, v135
	ds_read_b128 v[162:165], v0
	ds_read_b128 v[166:169], v0 offset:1024
	ds_read_b128 v[170:173], v0 offset:2048
	ds_read_b128 v[174:177], v0 offset:3072
	v_lshl_add_u64 v[142:143], s[18:19], 0, v[138:139]
	s_add_i32 m0, s25, 0xc000
	ds_read_b128 v[178:181], v144
	ds_read_b128 v[182:185], v144 offset:1024
	ds_read_b128 v[186:189], v144 offset:2048
	ds_read_b128 v[190:193], v144 offset:3072
	ds_read_b128 v[194:197], v144 offset:4096
	ds_read_b128 v[198:201], v144 offset:5120
	ds_read_b128 v[202:205], v144 offset:6144
	ds_read_b128 v[222:225], v144 offset:7168
	global_load_lds_dwordx4 v[142:143], off
	v_lshl_add_u64 v[142:143], s[18:19], 0, v[140:141]
	s_add_i32 m0, s25, 0xe000
	s_nop 0
	global_load_lds_dwordx4 v[142:143], off
	s_waitcnt vmcnt(8)
	s_waitcnt lgkmcnt(0)
	s_setprio 0
	s_barrier
	v_mfma_f32_16x16x32_bf16 v[126:129], v[146:149], v[178:181], v[126:129]
	v_mfma_f32_16x16x32_bf16 v[122:125], v[154:157], v[178:181], v[122:125]
	v_mfma_f32_16x16x32_bf16 v[110:113], v[146:149], v[186:189], v[110:113]
	v_mfma_f32_16x16x32_bf16 v[106:109], v[154:157], v[186:189], v[106:109]
	v_mfma_f32_16x16x32_bf16 v[94:97], v[146:149], v[194:197], v[94:97]
	v_mfma_f32_16x16x32_bf16 v[90:93], v[154:157], v[194:197], v[90:93]
	v_mfma_f32_16x16x32_bf16 v[78:81], v[146:149], v[202:205], v[78:81]
	v_mfma_f32_16x16x32_bf16 v[74:77], v[154:157], v[202:205], v[74:77]
	v_mfma_f32_16x16x32_bf16 v[126:129], v[150:153], v[182:185], v[126:129]
	v_mfma_f32_16x16x32_bf16 v[122:125], v[158:161], v[182:185], v[122:125]
	v_mfma_f32_16x16x32_bf16 v[110:113], v[150:153], v[190:193], v[110:113]
	v_mfma_f32_16x16x32_bf16 v[106:109], v[158:161], v[190:193], v[106:109]
	v_mfma_f32_16x16x32_bf16 v[94:97], v[150:153], v[198:201], v[94:97]
	v_mfma_f32_16x16x32_bf16 v[90:93], v[158:161], v[198:201], v[90:93]
	v_mfma_f32_16x16x32_bf16 v[78:81], v[150:153], v[222:225], v[78:81]
	v_mfma_f32_16x16x32_bf16 v[74:77], v[158:161], v[222:225], v[74:77]
	v_mfma_f32_16x16x32_bf16 v[118:121], v[162:165], v[178:181], v[118:121]
	v_mfma_f32_16x16x32_bf16 v[114:117], v[170:173], v[178:181], v[114:117]
	v_mfma_f32_16x16x32_bf16 v[102:105], v[162:165], v[186:189], v[102:105]
	v_mfma_f32_16x16x32_bf16 v[98:101], v[170:173], v[186:189], v[98:101]
	v_mfma_f32_16x16x32_bf16 v[86:89], v[162:165], v[194:197], v[86:89]
	v_mfma_f32_16x16x32_bf16 v[82:85], v[170:173], v[194:197], v[82:85]
	v_mfma_f32_16x16x32_bf16 v[70:73], v[162:165], v[202:205], v[70:73]
	v_mfma_f32_16x16x32_bf16 v[66:69], v[170:173], v[202:205], v[66:69]
	v_mfma_f32_16x16x32_bf16 v[118:121], v[166:169], v[182:185], v[118:121]
	v_mfma_f32_16x16x32_bf16 v[114:117], v[174:177], v[182:185], v[114:117]
	v_mfma_f32_16x16x32_bf16 v[102:105], v[166:169], v[190:193], v[102:105]
	v_mfma_f32_16x16x32_bf16 v[98:101], v[174:177], v[190:193], v[98:101]
	v_mfma_f32_16x16x32_bf16 v[86:89], v[166:169], v[198:201], v[86:89]
	v_mfma_f32_16x16x32_bf16 v[82:85], v[174:177], v[198:201], v[82:85]
	v_mfma_f32_16x16x32_bf16 v[70:73], v[166:169], v[222:225], v[70:73]
	v_mfma_f32_16x16x32_bf16 v[66:69], v[174:177], v[222:225], v[66:69]
	s_barrier
	s_setprio 1
	s_add_i32 s18, s47, s24
	v_lshl_add_u64 v[142:143], s[20:21], 0, v[130:131]
	s_mov_b32 m0, s18
	ds_read_b128 v[178:181], v144 offset:16384
	ds_read_b128 v[182:185], v144 offset:17408
	ds_read_b128 v[186:189], v144 offset:18432
	ds_read_b128 v[190:193], v144 offset:19456
	ds_read_b128 v[194:197], v144 offset:20480
	ds_read_b128 v[198:201], v144 offset:21504
	ds_read_b128 v[202:205], v144 offset:22528
	ds_read_b128 v[222:225], v144 offset:23552
	global_load_lds_dwordx4 v[142:143], off
	s_add_i32 m0, s18, 0x2000
	s_add_u32 s18, s20, 0xb0000
	v_lshl_add_u64 v[206:207], s[20:21], 0, v[132:133]
	s_addc_u32 s19, s21, 0
	s_add_i32 s47, s48, s24
	global_load_lds_dwordx4 v[206:207], off
	v_lshl_add_u64 v[218:219], s[18:19], 0, v[130:131]
	s_mov_b32 m0, s47
	v_lshl_add_u64 v[226:227], s[22:23], 0, v[132:133]
	global_load_lds_dwordx4 v[218:219], off
	v_lshl_add_u64 v[218:219], s[18:19], 0, v[132:133]
	s_add_i32 m0, s47, 0x2000
	s_nop 0
	global_load_lds_dwordx4 v[218:219], off
	v_lshl_add_u64 v[218:219], s[22:23], 0, v[130:131]
	s_mov_b32 m0, s25
	s_nop 0
	global_load_lds_dwordx4 v[218:219], off
	s_mov_b32 m0, s26
	s_nop 0
	global_load_lds_dwordx4 v[226:227], off
	s_waitcnt vmcnt(8)
	s_waitcnt lgkmcnt(0)
	s_setprio 0
	s_barrier
	v_mfma_f32_16x16x32_bf16 v[62:65], v[146:149], v[178:181], v[62:65]
	v_mfma_f32_16x16x32_bf16 v[58:61], v[154:157], v[178:181], v[58:61]
	v_mfma_f32_16x16x32_bf16 v[46:49], v[146:149], v[186:189], v[46:49]
	v_mfma_f32_16x16x32_bf16 v[42:45], v[154:157], v[186:189], v[42:45]
	v_mfma_f32_16x16x32_bf16 v[30:33], v[146:149], v[194:197], v[30:33]
	v_mfma_f32_16x16x32_bf16 v[26:29], v[154:157], v[194:197], v[26:29]
	v_mfma_f32_16x16x32_bf16 v[14:17], v[146:149], v[202:205], v[14:17]
	v_mfma_f32_16x16x32_bf16 v[10:13], v[154:157], v[202:205], v[10:13]
	v_mfma_f32_16x16x32_bf16 v[62:65], v[150:153], v[182:185], v[62:65]
	v_mfma_f32_16x16x32_bf16 v[58:61], v[158:161], v[182:185], v[58:61]
	v_mfma_f32_16x16x32_bf16 v[46:49], v[150:153], v[190:193], v[46:49]
	v_mfma_f32_16x16x32_bf16 v[42:45], v[158:161], v[190:193], v[42:45]
	v_mfma_f32_16x16x32_bf16 v[30:33], v[150:153], v[198:201], v[30:33]
	v_mfma_f32_16x16x32_bf16 v[26:29], v[158:161], v[198:201], v[26:29]
	v_mfma_f32_16x16x32_bf16 v[14:17], v[150:153], v[222:225], v[14:17]
	v_mfma_f32_16x16x32_bf16 v[10:13], v[158:161], v[222:225], v[10:13]
	v_mfma_f32_16x16x32_bf16 v[54:57], v[162:165], v[178:181], v[54:57]
	v_mfma_f32_16x16x32_bf16 v[50:53], v[170:173], v[178:181], v[50:53]
	v_mfma_f32_16x16x32_bf16 v[38:41], v[162:165], v[186:189], v[38:41]
	v_mfma_f32_16x16x32_bf16 v[34:37], v[170:173], v[186:189], v[34:37]
	v_mfma_f32_16x16x32_bf16 v[22:25], v[162:165], v[194:197], v[22:25]
	v_mfma_f32_16x16x32_bf16 v[18:21], v[170:173], v[194:197], v[18:21]
	v_mfma_f32_16x16x32_bf16 v[6:9], v[162:165], v[202:205], v[6:9]
	v_mfma_f32_16x16x32_bf16 v[2:5], v[170:173], v[202:205], v[2:5]
	v_mfma_f32_16x16x32_bf16 v[54:57], v[166:169], v[182:185], v[54:57]
	v_mfma_f32_16x16x32_bf16 v[50:53], v[174:177], v[182:185], v[50:53]
	v_mfma_f32_16x16x32_bf16 v[38:41], v[166:169], v[190:193], v[38:41]
	v_mfma_f32_16x16x32_bf16 v[34:37], v[174:177], v[190:193], v[34:37]
	v_mfma_f32_16x16x32_bf16 v[22:25], v[166:169], v[198:201], v[22:25]
	v_mfma_f32_16x16x32_bf16 v[18:21], v[174:177], v[198:201], v[18:21]
	v_mfma_f32_16x16x32_bf16 v[6:9], v[166:169], v[222:225], v[6:9]
	v_mfma_f32_16x16x32_bf16 v[2:5], v[174:177], v[222:225], v[2:5]
	s_barrier
	s_setprio 1
	s_add_i32 s47, 0, 0x18000
	v_add_u32_e32 v0, s47, v135
	s_add_i32 s48, 0, 0x1c000
	ds_read_b128 v[146:149], v0
	ds_read_b128 v[150:153], v0 offset:1024
	ds_read_b128 v[154:157], v0 offset:2048
	ds_read_b128 v[158:161], v0 offset:3072
	v_add_u32_e32 v0, s48, v135
	ds_read_b128 v[162:165], v0
	ds_read_b128 v[166:169], v0 offset:1024
	ds_read_b128 v[170:173], v0 offset:2048
	ds_read_b128 v[174:177], v0 offset:3072
	s_add_u32 s18, s22, 0xb0000
	s_addc_u32 s19, s23, 0
	s_mov_b32 m0, s27
	v_lshl_add_u64 v[228:229], s[18:19], 0, v[130:131]
	ds_read_b128 v[178:181], v144 offset:32768
	ds_read_b128 v[182:185], v144 offset:33792
	ds_read_b128 v[186:189], v144 offset:34816
	ds_read_b128 v[190:193], v144 offset:35840
	ds_read_b128 v[194:197], v144 offset:36864
	ds_read_b128 v[198:201], v144 offset:37888
	ds_read_b128 v[202:205], v144 offset:38912
	ds_read_b128 v[222:225], v144 offset:39936
	global_load_lds_dwordx4 v[228:229], off
	v_lshl_add_u64 v[228:229], s[18:19], 0, v[132:133]
	s_mov_b32 m0, s28
	s_nop 0
	global_load_lds_dwordx4 v[228:229], off
	s_waitcnt vmcnt(8)
	s_waitcnt lgkmcnt(0)
	s_setprio 0
	s_barrier
	v_mfma_f32_16x16x32_bf16 v[126:129], v[146:149], v[178:181], v[126:129]
	v_mfma_f32_16x16x32_bf16 v[122:125], v[154:157], v[178:181], v[122:125]
	v_mfma_f32_16x16x32_bf16 v[110:113], v[146:149], v[186:189], v[110:113]
	v_mfma_f32_16x16x32_bf16 v[106:109], v[154:157], v[186:189], v[106:109]
	v_mfma_f32_16x16x32_bf16 v[94:97], v[146:149], v[194:197], v[94:97]
	v_mfma_f32_16x16x32_bf16 v[90:93], v[154:157], v[194:197], v[90:93]
	v_mfma_f32_16x16x32_bf16 v[78:81], v[146:149], v[202:205], v[78:81]
	v_mfma_f32_16x16x32_bf16 v[74:77], v[154:157], v[202:205], v[74:77]
	v_mfma_f32_16x16x32_bf16 v[126:129], v[150:153], v[182:185], v[126:129]
	v_mfma_f32_16x16x32_bf16 v[122:125], v[158:161], v[182:185], v[122:125]
	v_mfma_f32_16x16x32_bf16 v[110:113], v[150:153], v[190:193], v[110:113]
	v_mfma_f32_16x16x32_bf16 v[106:109], v[158:161], v[190:193], v[106:109]
	v_mfma_f32_16x16x32_bf16 v[94:97], v[150:153], v[198:201], v[94:97]
	v_mfma_f32_16x16x32_bf16 v[90:93], v[158:161], v[198:201], v[90:93]
	v_mfma_f32_16x16x32_bf16 v[78:81], v[150:153], v[222:225], v[78:81]
	v_mfma_f32_16x16x32_bf16 v[74:77], v[158:161], v[222:225], v[74:77]
	v_mfma_f32_16x16x32_bf16 v[118:121], v[162:165], v[178:181], v[118:121]
	v_mfma_f32_16x16x32_bf16 v[114:117], v[170:173], v[178:181], v[114:117]
	v_mfma_f32_16x16x32_bf16 v[102:105], v[162:165], v[186:189], v[102:105]
	v_mfma_f32_16x16x32_bf16 v[98:101], v[170:173], v[186:189], v[98:101]
	v_mfma_f32_16x16x32_bf16 v[86:89], v[162:165], v[194:197], v[86:89]
	v_mfma_f32_16x16x32_bf16 v[82:85], v[170:173], v[194:197], v[82:85]
	v_mfma_f32_16x16x32_bf16 v[70:73], v[162:165], v[202:205], v[70:73]
	v_mfma_f32_16x16x32_bf16 v[66:69], v[170:173], v[202:205], v[66:69]
	v_mfma_f32_16x16x32_bf16 v[118:121], v[166:169], v[182:185], v[118:121]
	v_mfma_f32_16x16x32_bf16 v[114:117], v[174:177], v[182:185], v[114:117]
	v_mfma_f32_16x16x32_bf16 v[102:105], v[166:169], v[190:193], v[102:105]
	v_mfma_f32_16x16x32_bf16 v[98:101], v[174:177], v[190:193], v[98:101]
	v_mfma_f32_16x16x32_bf16 v[86:89], v[166:169], v[198:201], v[86:89]
	v_mfma_f32_16x16x32_bf16 v[82:85], v[174:177], v[198:201], v[82:85]
	v_mfma_f32_16x16x32_bf16 v[70:73], v[166:169], v[222:225], v[70:73]
	v_mfma_f32_16x16x32_bf16 v[66:69], v[174:177], v[222:225], v[66:69]
	s_barrier
	s_setprio 1
	s_add_i32 s18, s47, s24
	v_lshl_add_u64 v[142:143], v[142:143], 0, s[44:45]
	s_mov_b32 m0, s18
	ds_read_b128 v[178:181], v144 offset:49152
	ds_read_b128 v[182:185], v144 offset:50176
	ds_read_b128 v[186:189], v144 offset:51200
	ds_read_b128 v[190:193], v144 offset:52224
	ds_read_b128 v[194:197], v144 offset:53248
	ds_read_b128 v[198:201], v144 offset:54272
	ds_read_b128 v[202:205], v144 offset:55296
	ds_read_b128 v[222:225], v144 offset:56320
	global_load_lds_dwordx4 v[142:143], off
	s_add_i32 m0, s18, 0x2000
	s_add_u32 s18, s20, 0xb0080
	v_lshl_add_u64 v[142:143], v[206:207], 0, s[44:45]
	s_addc_u32 s19, s21, 0
	s_add_i32 s20, s48, s24
	global_load_lds_dwordx4 v[142:143], off
	v_lshl_add_u64 v[142:143], s[18:19], 0, v[130:131]
	s_mov_b32 m0, s20
	s_nop 0
	global_load_lds_dwordx4 v[142:143], off
	v_lshl_add_u64 v[142:143], s[18:19], 0, v[132:133]
	s_add_i32 m0, s20, 0x2000
	s_nop 0
	global_load_lds_dwordx4 v[142:143], off
	v_lshl_add_u64 v[142:143], v[218:219], 0, s[44:45]
	s_mov_b32 m0, s31
	s_nop 0
	global_load_lds_dwordx4 v[142:143], off
	v_lshl_add_u64 v[142:143], v[226:227], 0, s[44:45]
	s_mov_b32 m0, s33
	s_nop 0
	global_load_lds_dwordx4 v[142:143], off
	s_waitcnt vmcnt(8)
	s_waitcnt lgkmcnt(0)
	s_setprio 0
	s_barrier
	v_mfma_f32_16x16x32_bf16 v[62:65], v[146:149], v[178:181], v[62:65]
	v_mfma_f32_16x16x32_bf16 v[58:61], v[154:157], v[178:181], v[58:61]
	v_mfma_f32_16x16x32_bf16 v[46:49], v[146:149], v[186:189], v[46:49]
	v_mfma_f32_16x16x32_bf16 v[42:45], v[154:157], v[186:189], v[42:45]
	v_mfma_f32_16x16x32_bf16 v[30:33], v[146:149], v[194:197], v[30:33]
	v_mfma_f32_16x16x32_bf16 v[26:29], v[154:157], v[194:197], v[26:29]
	v_mfma_f32_16x16x32_bf16 v[14:17], v[146:149], v[202:205], v[14:17]
	v_mfma_f32_16x16x32_bf16 v[10:13], v[154:157], v[202:205], v[10:13]
	v_mfma_f32_16x16x32_bf16 v[62:65], v[150:153], v[182:185], v[62:65]
	v_mfma_f32_16x16x32_bf16 v[58:61], v[158:161], v[182:185], v[58:61]
	v_mfma_f32_16x16x32_bf16 v[46:49], v[150:153], v[190:193], v[46:49]
	v_mfma_f32_16x16x32_bf16 v[42:45], v[158:161], v[190:193], v[42:45]
	v_mfma_f32_16x16x32_bf16 v[30:33], v[150:153], v[198:201], v[30:33]
	v_mfma_f32_16x16x32_bf16 v[26:29], v[158:161], v[198:201], v[26:29]
	v_mfma_f32_16x16x32_bf16 v[14:17], v[150:153], v[222:225], v[14:17]
	v_mfma_f32_16x16x32_bf16 v[10:13], v[158:161], v[222:225], v[10:13]
	v_mfma_f32_16x16x32_bf16 v[54:57], v[162:165], v[178:181], v[54:57]
	v_mfma_f32_16x16x32_bf16 v[50:53], v[170:173], v[178:181], v[50:53]
	v_mfma_f32_16x16x32_bf16 v[38:41], v[162:165], v[186:189], v[38:41]
	v_mfma_f32_16x16x32_bf16 v[34:37], v[170:173], v[186:189], v[34:37]
	v_mfma_f32_16x16x32_bf16 v[22:25], v[162:165], v[194:197], v[22:25]
	v_mfma_f32_16x16x32_bf16 v[18:21], v[170:173], v[194:197], v[18:21]
	v_mfma_f32_16x16x32_bf16 v[6:9], v[162:165], v[202:205], v[6:9]
	v_mfma_f32_16x16x32_bf16 v[2:5], v[170:173], v[202:205], v[2:5]
	v_mfma_f32_16x16x32_bf16 v[54:57], v[166:169], v[182:185], v[54:57]
	v_mfma_f32_16x16x32_bf16 v[50:53], v[174:177], v[182:185], v[50:53]
	v_mfma_f32_16x16x32_bf16 v[38:41], v[166:169], v[190:193], v[38:41]
	v_mfma_f32_16x16x32_bf16 v[34:37], v[174:177], v[190:193], v[34:37]
	v_mfma_f32_16x16x32_bf16 v[22:25], v[166:169], v[198:201], v[22:25]
	v_mfma_f32_16x16x32_bf16 v[18:21], v[174:177], v[198:201], v[18:21]
	v_mfma_f32_16x16x32_bf16 v[6:9], v[166:169], v[222:225], v[6:9]
	v_mfma_f32_16x16x32_bf16 v[2:5], v[174:177], v[222:225], v[2:5]
	s_barrier
	s_setprio 1
	s_add_i32 s46, s46, 2
	s_add_u32 s17, s17, 0x100
	s_addc_u32 s42, s42, 0
	s_cmp_gt_u32 s46, 41
	s_mov_b64 s[18:19], s[2:3]
	s_cbranch_scc0 .LBB0_849
	s_and_b64 vcc, exec, s[12:13]
	s_cbranch_vccz .LBB0_852
	s_barrier
